# speedup vs baseline: 1.0128x; 1.0009x over previous
; __device__ __forceinline__ void gemm_tile(const GemmArgs& ga, int wgid, int next_wgid, bool prefetched, u16* shm, unsigned char* ws, int wv_) {
;     ...
;   if (next_wgid >= 0) {
;     int nbrow, nbcol, npn;
;     tilemap(next_wgid, nbrow, nbcol, npn);
;     const u16* An = ga.A;
;     const u16* Bn = ga.Bt;
;     if (ga.epi == EPI_LORA) { int koff = (npn >= 20) ? 256 : 0; An += koff; Bn += koff; }
;     if (ga.epi & EPI_KSPLIT4) { int nks = npn & 3; npn >>= 2; nbcol = npn * BM; An += nks * ga.K; Bn += nks * ga.K; }
;     ...
;   const float* e_ss = (const float*)(ws + OFF_SS) + (size_t)(ga.ss_idx < 0 ? 0 : ga.ss_idx) * T_;
;   float* e_ssn = (float*)(ws + OFF_SS) + (size_t)(ga.ssn_idx < 0 ? 0 : ga.ssn_idx) * T_;
;   u16* e_outb = (u16*)(ws + (size_t)ga.out_off * 256) + (size_t)ks * ((size_t)T_ * 512);
;   const int epi = ga.epi & 0xff;
;   const int rbase = brow + wr2 * 64 + fq * 4;
;   const int lc4 = (wc * 16 + fr) * 4;
;   if (epi == EPI_SWIGLU) {
;     const int oc = pn * HALF + (wc * 16 + fr) * 2;
;     float sc[2][4][4];
;     _Pragma("unroll") for (int ai = 0; ai < 2; ++ai)
;       _Pragma("unroll") for (int m = 0; m < 4; ++m)
;         _Pragma("unroll") for (int j = 0; j < 4; ++j) sc[ai][m][j] = e_ss[rbase + ai * HALF + m * 16 + j];
.LBB0_516:
	s_or_b64 exec, exec, s[2:3]
	v_readlane_b32 s8, v254, 58
	s_nop 3
	s_and_b32 s8, s8, 0xfffffffd
	s_cmp_eq_u32 s8, 0
	s_cbranch_scc0 .Lss_early_skip
	v_mbcnt_lo_u32_b32 v188, -1, 0
	v_mbcnt_hi_u32_b32 v188, -1, v188
	v_or_b32_e32 v188, s60, v188
	v_ashrrev_i32_e32 v189, 2, v188
	v_and_b32_e32 v189, 0xffffffc0, v189
	v_add_u32_e32 v189, s6, v189
	v_lshrrev_b32_e32 v188, 2, v188
	v_and_or_b32 v188, v188, 12, v189
	v_mov_b32_e32 v189, 0
	s_add_u32 s2, s78, 0x2b140000
	s_addc_u32 s3, s79, 0
	v_readlane_b32 s8, v254, 56
	v_readlane_b32 s9, v254, 57
	s_nop 3
	s_add_u32 s2, s2, s8
	s_addc_u32 s3, s3, s9
	v_lshl_add_u64 v[190:191], v[188:189], 2, s[2:3]
	global_load_dwordx4 v[208:211], v[190:191], off
	global_load_dwordx4 v[212:215], v[190:191], off offset:64
	global_load_dwordx4 v[216:219], v[190:191], off offset:128
	global_load_dwordx4 v[220:223], v[190:191], off offset:192
	global_load_dwordx4 v[224:227], v[190:191], off offset:512
	global_load_dwordx4 v[228:231], v[190:191], off offset:576
	global_load_dwordx4 v[232:235], v[190:191], off offset:640
	global_load_dwordx4 v[236:239], v[190:191], off offset:704
.Lss_early_skip:
	s_add_i32 s62, s62, s39
	s_cmp_ge_i32 s62, s63
	s_cselect_b64 s[18:19], -1, 0
	s_cmp_lt_i32 s62, s63
	s_cselect_b32 s2, s62, -1
	s_cmp_gt_i32 s2, -1
	s_cselect_b64 s[8:9], -1, 0
	v_writelane_b32 v254, s8, 54
	v_mov_b64_e32 v[184:185], v[132:133]
	s_cmp_lt_i32 s2, 0
	v_writelane_b32 v254, s9, 55
	v_mov_b64_e32 v[182:183], v[130:131]
	s_cbranch_scc1 .LBB0_521
	s_and_b32 s3, s2, 7
	v_mov_b32_e32 v0, s57
	v_mul_u32_u24_e32 v0, s3, v0
	s_lshr_b32 s2, s2, 3
	v_readfirstlane_b32 s3, v0
	s_add_i32 s3, s3, s2
	v_readlane_b32 s2, v254, 53
	s_mul_hi_u32 s2, s3, s2
	s_mul_i32 s8, s2, s10
	s_sub_i32 s8, s3, s8
	s_add_i32 s9, s2, 1
	s_sub_i32 s13, s8, s10
	s_cmp_ge_u32 s8, s10
	s_cselect_b32 s2, s9, s2
	s_cselect_b32 s8, s13, s8
	s_add_i32 s9, s2, 1
	s_cmp_ge_u32 s8, s10
	s_cselect_b32 s2, s9, s2
	s_lshl_b32 s8, s2, 3
	s_sub_i32 s9, 32, s8
	s_min_i32 s9, s9, 8
	s_abs_i32 s13, s9
	v_cvt_f32_u32_e32 v0, s13
	s_sub_i32 s14, 0, s13
	s_mul_i32 s2, s2, s10
	s_sub_i32 s15, s3, s2
	v_rcp_iflag_f32_e32 v0, v0
	s_abs_i32 s3, s15
	s_xor_b32 s2, s15, s9
	s_ashr_i32 s2, s2, 31
	v_mul_f32_e32 v0, 0x4f7ffffe, v0
	v_cvt_u32_f32_e32 v0, v0
	s_mov_b64 s[22:23], s[18:19]
	v_readlane_b32 s18, v254, 36
	v_readlane_b32 s19, v254, 37
	v_readfirstlane_b32 s16, v0
	s_mul_i32 s14, s14, s16
	s_mul_hi_u32 s14, s16, s14
	s_add_i32 s16, s16, s14
	s_mul_hi_u32 s14, s3, s16
	s_mul_i32 s16, s14, s13
	s_sub_i32 s3, s3, s16
	s_add_i32 s16, s14, 1
	s_sub_i32 s17, s3, s13
	s_cmp_ge_u32 s3, s13
	s_cselect_b32 s14, s16, s14
	s_cselect_b32 s3, s17, s3
	s_add_i32 s16, s14, 1
	s_cmp_ge_u32 s3, s13
	s_cselect_b32 s3, s16, s14
	s_xor_b32 s3, s3, s2
	s_sub_i32 s17, s3, s2
	s_cmp_gt_i32 s17, 19
	s_cselect_b64 s[2:3], -1, 0
	s_and_b64 s[2:3], s[18:19], s[2:3]
	s_and_b64 s[2:3], s[2:3], exec
	s_cselect_b32 s13, 0x200, 0
	s_add_u32 s2, s88, s13
	s_addc_u32 s3, s89, 0
	v_readlane_b32 s18, v254, 30
	v_readlane_b32 s19, v254, 31
	s_add_u32 s13, s18, s13
	s_addc_u32 s14, s19, 0
	v_readlane_b32 s18, v254, 34
	v_readlane_b32 s19, v254, 35
	s_andn2_b64 vcc, exec, s[18:19]
	s_cbranch_vccnz .LBB0_519
	s_and_b32 s18, s17, 3
	v_mov_b32_e32 v0, s35
	v_mul_u32_u24_e32 v0, s18, v0
	s_lshl_b32 s16, s17, 6
	v_readfirstlane_b32 s18, v0
	s_and_b32 s16, s16, 0xffffff00
	s_lshl_b32 s18, s18, 1
	s_add_u32 s2, s2, s18
	s_addc_u32 s3, s3, 0
	s_add_u32 s13, s13, s18
	s_addc_u32 s14, s14, 0
	s_branch .LBB0_520

; __device__ __forceinline__ void gemm_tile(const GemmArgs& ga, int wgid, int next_wgid, bool prefetched, u16* shm, unsigned char* ws, int wv_) {
;     ...
;     _Pragma("unroll") for (int ai = 0; ai < 2; ++ai)
;       _Pragma("unroll") for (int m = 0; m < 4; ++m)
;         _Pragma("unroll") for (int j = 0; j < 4; ++j) sc[ai][m][j] = (epi == EPI_Z) ? e_ss[rbase + ai * HALF + m * 16 + j] : 0.f;
;     _Pragma("unroll") for (int ai = 0; ai < 2; ++ai)
;       _Pragma("unroll") for (int m = 0; m < 4; ++m)
;         _Pragma("unroll") for (int j = 0; j < 4; ++j) {
;           int row = rbase + ai * HALF + m * 16 + j;
;           float s = (epi == EPI_Z) ? rsqrtf(sc[ai][m][j] * (1.f / D_) + 1e-6f) : 1.f;
.LBB0_1097:
	v_ashrrev_i32_e32 v169, 31, v168
	v_lshl_add_u64 v[0:1], v[168:169], 2, s[68:69]
	v_readlane_b32 s100, v254, 54
	s_nop 3
	s_cmp_eq_u32 s100, 0
	s_cbranch_scc1 .Lssw0_z
	s_waitcnt vmcnt(14)
	s_branch .Lsswd_z

; __device__ __forceinline__ void gemm_tile(const GemmArgs& ga, int wgid, int next_wgid, bool prefetched, u16* shm, unsigned char* ws, int wv_) {
;     ...
;         _Pragma("unroll") for (int j = 0; j < 4; ++j) sc[ai][m][j] = (epi == EPI_Z) ? e_ss[rbase + ai * HALF + m * 16 + j] : 0.f;
;     _Pragma("unroll") for (int ai = 0; ai < 2; ++ai)
;       _Pragma("unroll") for (int m = 0; m < 4; ++m)
;         _Pragma("unroll") for (int j = 0; j < 4; ++j) {
;           int row = rbase + ai * HALF + m * 16 + j;
;           float s = (epi == EPI_Z) ? rsqrtf(sc[ai][m][j] * (1.f / D_) + 1e-6f) : 1.f;
.Lsswd_z:
	v_mov_b32_e32 v0, v208
	v_fmamk_f32 v172, v0, 0x3a000000, v175
	s_and_b64 vcc, exec, s[6:7]
	s_cbranch_vccnz .LBB0_1057

; __device__ __forceinline__ void gemm_tile(const GemmArgs& ga, int wgid, int next_wgid, bool prefetched, u16* shm, unsigned char* ws, int wv_) {
;     ...
;   const int rbase = brow + wr2 * 64 + fq * 4;
;   const int lc4 = (wc * 16 + fr) * 4;
;   if (epi == EPI_SWIGLU) {
;     const int oc = pn * HALF + (wc * 16 + fr) * 2;
;     float sc[2][4][4];
;     _Pragma("unroll") for (int ai = 0; ai < 2; ++ai)
;       _Pragma("unroll") for (int m = 0; m < 4; ++m)
;         _Pragma("unroll") for (int j = 0; j < 4; ++j) sc[ai][m][j] = e_ss[rbase + ai * HALF + m * 16 + j];
;     _Pragma("unroll") for (int ai = 0; ai < 2; ++ai)
;       _Pragma("unroll") for (int m = 0; m < 4; ++m)
;         _Pragma("unroll") for (int j = 0; j < 4; ++j) {
;           int row = rbase + ai * HALF + m * 16 + j;
.LBB0_1263:
	s_lshl_b32 s2, s87, 7
	v_ashrrev_i32_e32 v169, 31, v168
	v_lshl_or_b32 v0, v187, 1, s2
	v_lshl_add_u64 v[132:133], v[168:169], 2, s[68:69]
	v_ashrrev_i32_e32 v1, 31, v0
	v_lshl_add_u64 v[128:129], v[0:1], 1, s[90:91]
	s_movk_i32 s8, 0x2c00
	v_mad_i64_i32 v[134:135], s[2:3], v168, s8, v[128:129]
	s_mov_b32 s2, 0x358637bd
	s_nop 0
	v_mov_b64_e32 v[130:131], s[2:3]
	s_mov_b32 s12, 0x3a000000
	v_or_b32_e32 v8, 1, v168
	v_or_b32_e32 v9, 2, v168
	v_or_b32_e32 v10, 3, v168
	v_or_b32_e32 v11, 16, v168
	v_or_b32_e32 v162, 17, v168
	v_or_b32_e32 v161, 18, v168
	v_or_b32_e32 v160, 19, v168
	v_or_b32_e32 v159, 32, v168
	v_or_b32_e32 v158, 33, v168
	v_or_b32_e32 v157, 34, v168
	v_or_b32_e32 v156, 35, v168
	v_or_b32_e32 v155, 48, v168
	v_or_b32_e32 v154, 49, v168
	v_or_b32_e32 v153, 50, v168
	v_or_b32_e32 v152, 51, v168
	v_add_u32_e32 v151, 0x80, v168
	v_add_u32_e32 v150, 0x81, v168
	v_add_u32_e32 v149, 0x82, v168
	v_add_u32_e32 v148, 0x83, v168
	v_add_u32_e32 v147, 0x90, v168
	v_add_u32_e32 v146, 0x91, v168
	v_add_u32_e32 v145, 0x92, v168
	v_add_u32_e32 v144, 0x93, v168
	v_add_u32_e32 v143, 0xa0, v168
	v_add_u32_e32 v142, 0xa1, v168
	v_add_u32_e32 v141, 0xa2, v168
	v_add_u32_e32 v140, 0xa3, v168
	v_add_u32_e32 v139, 0xb0, v168
	v_add_u32_e32 v138, 0xb1, v168
	v_add_u32_e32 v137, 0xb2, v168
	v_add_u32_e32 v136, 0xb3, v168
	v_readlane_b32 s100, v254, 54
	s_nop 3
	s_cmp_eq_u32 s100, 0
	s_cbranch_scc1 .Lssw0_s
	s_waitcnt vmcnt(14)
	s_branch .Lsswd_s

; __device__ __forceinline__ u32 pack2(float a, float b) { return (u32)f2bf(a) | ((u32)f2bf(b) << 16); }
; __device__ __forceinline__ float sigmoidf_(float x) { return __builtin_amdgcn_rcpf(1.f + __expf(-x)); }
; __device__ __forceinline__ void gemm_tile(const GemmArgs& ga, int wgid, int next_wgid, bool prefetched, u16* shm, unsigned char* ws, int wv_) {
;     ...
;     _Pragma("unroll") for (int ai = 0; ai < 2; ++ai)
;       _Pragma("unroll") for (int m = 0; m < 4; ++m)
;         _Pragma("unroll") for (int j = 0; j < 4; ++j) sc[ai][m][j] = e_ss[rbase + ai * HALF + m * 16 + j];
;     _Pragma("unroll") for (int ai = 0; ai < 2; ++ai)
;       _Pragma("unroll") for (int m = 0; m < 4; ++m)
;         _Pragma("unroll") for (int j = 0; j < 4; ++j) {
;           int row = rbase + ai * HALF + m * 16 + j;
;           float s = rsqrtf(sc[ai][m][j] * (1.f / D_) + 1e-6f);
;           float h2[2];
;           _Pragma("unroll") for (int n = 0; n < 2; ++n) {
;             float a1 = acc[ai][0][m][n][j] * s, a3 = acc[ai][1][m][n][j] * s;
;             h2[n] = a1 * sigmoidf_(a1) * a3;
;           }
;           *(u32*)(e_outb + (size_t)row * F_ + oc) = pack2(h2[0], h2[1]);
;         }
.Lsswd_s:
	v_mov_b64_e32 v[0:1], v[208:209]
	v_mov_b64_e32 v[2:3], v[210:211]
	v_pk_fma_f32 v[0:1], v[0:1], s[12:13], v[130:131] op_sel_hi:[1,0,0]
	s_nop 0
	v_pk_fma_f32 v[2:3], v[2:3], s[12:13], v[130:131] op_sel_hi:[1,0,0]
	v_rsq_f32_e32 v0, v0
	s_nop 0
	v_mul_f32_e32 v16, v116, v0
	v_mul_f32_e32 v18, 0xbfb8aa3b, v16
	v_exp_f32_e32 v18, v18
	v_mul_f32_e32 v17, v124, v0
	v_add_f32_e32 v18, 1.0, v18
	v_rcp_f32_e32 v18, v18
	s_nop 0
	v_mul_f32_e32 v16, v16, v18
	v_mul_f32_e32 v16, v17, v16
	v_mul_f32_e32 v17, v112, v0
	v_mul_f32_e32 v18, 0xbfb8aa3b, v17
	v_exp_f32_e32 v18, v18
	v_mul_f32_e32 v0, v120, v0
	v_add_f32_e32 v18, 1.0, v18
	v_rcp_f32_e32 v18, v18
	s_nop 0
	v_mul_f32_e32 v17, v17, v18
	v_mul_f32_e32 v0, v0, v17
	v_cvt_pk_bf16_f32 v0, v16, v0
	global_store_dword v[134:135], v0, off
	v_rsq_f32_e32 v0, v1
	s_nop 0
	v_mul_f32_e32 v1, v117, v0
	v_mul_f32_e32 v17, 0xbfb8aa3b, v1
	v_exp_f32_e32 v17, v17
	v_mul_f32_e32 v16, v125, v0
	v_mad_i64_i32 v[116:117], s[2:3], v11, s8, v[128:129]
	v_add_f32_e32 v17, 1.0, v17
	v_rcp_f32_e32 v17, v17
	s_nop 0
	v_mul_f32_e32 v1, v1, v17
	v_mul_f32_e32 v1, v16, v1
	v_mul_f32_e32 v16, v113, v0
	v_mul_f32_e32 v17, 0xbfb8aa3b, v16
	v_exp_f32_e32 v17, v17
	v_mul_f32_e32 v0, v121, v0
	v_add_f32_e32 v17, 1.0, v17
	v_rcp_f32_e32 v17, v17
	s_nop 0
	v_mul_f32_e32 v16, v16, v17
	v_mul_f32_e32 v0, v0, v16
	v_cvt_pk_bf16_f32 v16, v1, v0
	v_mad_i64_i32 v[0:1], s[2:3], v8, s8, v[128:129]
	v_rsq_f32_e32 v2, v2
	global_store_dword v[0:1], v16, off
	v_mad_i64_i32 v[0:1], s[2:3], v9, s8, v[128:129]
	v_mul_f32_e32 v8, v118, v2
	v_mul_f32_e32 v16, 0xbfb8aa3b, v8
	v_exp_f32_e32 v16, v16
	v_mul_f32_e32 v9, v126, v2
	v_add_f32_e32 v16, 1.0, v16
	v_rcp_f32_e32 v16, v16
	s_nop 0
	v_mul_f32_e32 v8, v8, v16
	v_mul_f32_e32 v8, v9, v8
	v_mul_f32_e32 v9, v114, v2
	v_mul_f32_e32 v16, 0xbfb8aa3b, v9
	v_exp_f32_e32 v16, v16
	v_mul_f32_e32 v2, v122, v2
	v_add_f32_e32 v16, 1.0, v16
	v_rcp_f32_e32 v16, v16
	s_nop 0
	v_mul_f32_e32 v9, v9, v16
	v_mul_f32_e32 v2, v2, v9
	v_cvt_pk_bf16_f32 v2, v8, v2
	global_store_dword v[0:1], v2, off
	v_rsq_f32_e32 v0, v3
	v_mov_b64_e32 v[16:17], v[236:237]
	v_mov_b64_e32 v[18:19], v[238:239]
	v_mul_f32_e32 v1, v119, v0
	v_mul_f32_e32 v3, 0xbfb8aa3b, v1
	v_exp_f32_e32 v3, v3
	v_mul_f32_e32 v2, v127, v0
	v_add_f32_e32 v3, 1.0, v3
	v_rcp_f32_e32 v3, v3
	s_nop 0
	v_mul_f32_e32 v1, v1, v3
	v_mul_f32_e32 v1, v2, v1
	v_mul_f32_e32 v2, v115, v0
	v_mov_b64_e32 v[112:113], v[212:213]
	v_mov_b64_e32 v[114:115], v[214:215]
	v_mul_f32_e32 v3, 0xbfb8aa3b, v2
	v_exp_f32_e32 v3, v3
	v_mul_f32_e32 v0, v123, v0
	v_add_f32_e32 v3, 1.0, v3
	v_rcp_f32_e32 v3, v3
	s_nop 0
	v_mul_f32_e32 v2, v2, v3
	v_mul_f32_e32 v0, v0, v2
	v_cvt_pk_bf16_f32 v2, v1, v0
	v_mad_i64_i32 v[0:1], s[2:3], v10, s8, v[128:129]
	global_store_dword v[0:1], v2, off
	v_pk_fma_f32 v[0:1], v[112:113], s[12:13], v[130:131] op_sel_hi:[1,0,0]
	s_nop 0
	s_nop 0
	v_rsq_f32_e32 v0, v0
	s_nop 0
	v_mul_f32_e32 v2, v100, v0
	v_mul_f32_e32 v8, 0xbfb8aa3b, v2
	v_exp_f32_e32 v8, v8
	v_mul_f32_e32 v3, v108, v0
	v_add_f32_e32 v8, 1.0, v8
	v_rcp_f32_e32 v8, v8
	s_nop 0
	v_mul_f32_e32 v2, v2, v8
	v_mul_f32_e32 v2, v3, v2
	v_mul_f32_e32 v3, v96, v0
	v_mul_f32_e32 v8, 0xbfb8aa3b, v3
	v_exp_f32_e32 v8, v8
	v_mul_f32_e32 v0, v104, v0
	v_add_f32_e32 v8, 1.0, v8
	v_rcp_f32_e32 v8, v8
	s_nop 0
	v_mul_f32_e32 v3, v3, v8
	v_mul_f32_e32 v0, v0, v3
	v_cvt_pk_bf16_f32 v0, v2, v0
	global_store_dword v[116:117], v0, off
	v_rsq_f32_e32 v0, v1
	s_nop 0
	v_mul_f32_e32 v1, v101, v0
	v_mul_f32_e32 v3, 0xbfb8aa3b, v1
	v_exp_f32_e32 v3, v3
	v_mul_f32_e32 v2, v109, v0
	v_add_f32_e32 v3, 1.0, v3
	v_rcp_f32_e32 v3, v3
	s_nop 0
	v_mul_f32_e32 v1, v1, v3
	v_mul_f32_e32 v1, v2, v1
	v_mul_f32_e32 v2, v97, v0
	v_mul_f32_e32 v3, 0xbfb8aa3b, v2
	v_exp_f32_e32 v3, v3
	v_mul_f32_e32 v0, v105, v0
	v_mad_i64_i32 v[96:97], s[2:3], v159, s8, v[128:129]
	v_add_f32_e32 v3, 1.0, v3
	v_rcp_f32_e32 v3, v3
	s_nop 0
	v_mul_f32_e32 v2, v2, v3
	v_mul_f32_e32 v0, v0, v2
	v_cvt_pk_bf16_f32 v2, v1, v0
	v_mad_i64_i32 v[0:1], s[2:3], v162, s8, v[128:129]
	global_store_dword v[0:1], v2, off
	v_pk_fma_f32 v[2:3], v[114:115], s[12:13], v[130:131] op_sel_hi:[1,0,0]
	v_mad_i64_i32 v[0:1], s[2:3], v161, s8, v[128:129]
	s_nop 0
	v_rsq_f32_e32 v2, v2
	s_nop 0
	v_mul_f32_e32 v8, v102, v2
	v_mul_f32_e32 v10, 0xbfb8aa3b, v8
	v_exp_f32_e32 v10, v10
	v_mul_f32_e32 v9, v110, v2
	v_add_f32_e32 v10, 1.0, v10
	v_rcp_f32_e32 v10, v10
	s_nop 0
	v_mul_f32_e32 v8, v8, v10
	v_mul_f32_e32 v8, v9, v8
	v_mul_f32_e32 v9, v98, v2
	v_mul_f32_e32 v10, 0xbfb8aa3b, v9
	v_exp_f32_e32 v10, v10
	v_mul_f32_e32 v2, v106, v2
	v_add_f32_e32 v10, 1.0, v10
	v_rcp_f32_e32 v10, v10
	s_nop 0
	v_mul_f32_e32 v9, v9, v10
	v_mul_f32_e32 v2, v2, v9
	v_cvt_pk_bf16_f32 v2, v8, v2
	global_store_dword v[0:1], v2, off
	v_rsq_f32_e32 v0, v3
	s_nop 0
	v_mul_f32_e32 v1, v103, v0
	v_mul_f32_e32 v3, 0xbfb8aa3b, v1
	v_exp_f32_e32 v3, v3
	v_mul_f32_e32 v2, v111, v0
	v_add_f32_e32 v3, 1.0, v3
	v_rcp_f32_e32 v3, v3
	s_nop 0
	v_mul_f32_e32 v1, v1, v3
	v_mul_f32_e32 v1, v2, v1
	v_mul_f32_e32 v2, v99, v0
	v_mul_f32_e32 v3, 0xbfb8aa3b, v2
	v_exp_f32_e32 v3, v3
	v_mul_f32_e32 v0, v107, v0
	v_add_f32_e32 v3, 1.0, v3
	v_rcp_f32_e32 v3, v3
	s_nop 0
	v_mul_f32_e32 v2, v2, v3
	v_mul_f32_e32 v0, v0, v2
	v_cvt_pk_bf16_f32 v2, v1, v0
	v_mad_i64_i32 v[0:1], s[2:3], v160, s8, v[128:129]
	global_store_dword v[0:1], v2, off
	v_mov_b64_e32 v[0:1], v[216:217]
	v_mov_b64_e32 v[2:3], v[218:219]
	v_pk_fma_f32 v[0:1], v[0:1], s[12:13], v[130:131] op_sel_hi:[1,0,0]
	s_nop 0
	v_pk_fma_f32 v[2:3], v[2:3], s[12:13], v[130:131] op_sel_hi:[1,0,0]
	v_rsq_f32_e32 v0, v0
	s_nop 0
	v_mul_f32_e32 v8, v84, v0
; __device__ __forceinline__ u32 pack2(float a, float b) { return (u32)f2bf(a) | ((u32)f2bf(b) << 16); }
; __device__ __forceinline__ float sigmoidf_(float x) { return __builtin_amdgcn_rcpf(1.f + __expf(-x)); }
; __device__ __forceinline__ void gemm_tile(const GemmArgs& ga, int wgid, int next_wgid, bool prefetched, u16* shm, unsigned char* ws, int wv_) {
;     ...
;     _Pragma("unroll") for (int ai = 0; ai < 2; ++ai)
;       _Pragma("unroll") for (int m = 0; m < 4; ++m)
;         _Pragma("unroll") for (int j = 0; j < 4; ++j) sc[ai][m][j] = e_ss[rbase + ai * HALF + m * 16 + j];
;     _Pragma("unroll") for (int ai = 0; ai < 2; ++ai)
;       _Pragma("unroll") for (int m = 0; m < 4; ++m)
;         _Pragma("unroll") for (int j = 0; j < 4; ++j) {
;           int row = rbase + ai * HALF + m * 16 + j;
;           float s = rsqrtf(sc[ai][m][j] * (1.f / D_) + 1e-6f);
;           float h2[2];
;           _Pragma("unroll") for (int n = 0; n < 2; ++n) {
;             float a1 = acc[ai][0][m][n][j] * s, a3 = acc[ai][1][m][n][j] * s;
;             h2[n] = a1 * sigmoidf_(a1) * a3;
;           }
;           *(u32*)(e_outb + (size_t)row * F_ + oc) = pack2(h2[0], h2[1]);
;         }
	v_mul_f32_e32 v10, 0xbfb8aa3b, v8
	v_exp_f32_e32 v10, v10
	v_mul_f32_e32 v9, v92, v0
	v_add_f32_e32 v10, 1.0, v10
	v_rcp_f32_e32 v10, v10
	s_nop 0
	v_mul_f32_e32 v8, v8, v10
	v_mul_f32_e32 v8, v9, v8
	v_mul_f32_e32 v9, v80, v0
	v_mul_f32_e32 v10, 0xbfb8aa3b, v9
	v_exp_f32_e32 v10, v10
	v_mul_f32_e32 v0, v88, v0
	v_add_f32_e32 v10, 1.0, v10
	v_rcp_f32_e32 v10, v10
	s_nop 0
	v_mul_f32_e32 v9, v9, v10
	v_mul_f32_e32 v0, v0, v9
	v_cvt_pk_bf16_f32 v0, v8, v0
	global_store_dword v[96:97], v0, off
	v_rsq_f32_e32 v0, v1
	s_nop 0
	v_mul_f32_e32 v1, v85, v0
	v_mul_f32_e32 v9, 0xbfb8aa3b, v1
	v_exp_f32_e32 v9, v9
	v_mul_f32_e32 v8, v93, v0
	v_mad_i64_i32 v[84:85], s[2:3], v155, s8, v[128:129]
	v_add_f32_e32 v9, 1.0, v9
	v_rcp_f32_e32 v9, v9
	s_nop 0
	v_mul_f32_e32 v1, v1, v9
	v_mul_f32_e32 v1, v8, v1
	v_mul_f32_e32 v8, v81, v0
	v_mul_f32_e32 v9, 0xbfb8aa3b, v8
	v_exp_f32_e32 v9, v9
	v_mul_f32_e32 v0, v89, v0
	v_add_f32_e32 v9, 1.0, v9
	v_rcp_f32_e32 v9, v9
	s_nop 0
	v_mul_f32_e32 v8, v8, v9
	v_mul_f32_e32 v0, v0, v8
	v_cvt_pk_bf16_f32 v8, v1, v0
	v_mad_i64_i32 v[0:1], s[2:3], v158, s8, v[128:129]
	global_store_dword v[0:1], v8, off
	v_rsq_f32_e32 v2, v2
	v_mad_i64_i32 v[0:1], s[2:3], v157, s8, v[128:129]
	v_mul_f32_e32 v8, v86, v2
	v_mul_f32_e32 v10, 0xbfb8aa3b, v8
	v_exp_f32_e32 v10, v10
	v_mul_f32_e32 v9, v94, v2
	v_add_f32_e32 v10, 1.0, v10
	v_rcp_f32_e32 v10, v10
	s_nop 0
	v_mul_f32_e32 v8, v8, v10
	v_mul_f32_e32 v8, v9, v8
	v_mul_f32_e32 v9, v82, v2
	v_mul_f32_e32 v10, 0xbfb8aa3b, v9
	v_exp_f32_e32 v10, v10
	v_mul_f32_e32 v2, v90, v2
	v_add_f32_e32 v10, 1.0, v10
	v_rcp_f32_e32 v10, v10
	s_nop 0
	v_mul_f32_e32 v9, v9, v10
	v_mul_f32_e32 v2, v2, v9
	v_cvt_pk_bf16_f32 v2, v8, v2
	global_store_dword v[0:1], v2, off
	v_rsq_f32_e32 v0, v3
	s_nop 0
	v_mul_f32_e32 v1, v87, v0
	v_mul_f32_e32 v3, 0xbfb8aa3b, v1
	v_exp_f32_e32 v3, v3
	v_mul_f32_e32 v2, v95, v0
	v_add_f32_e32 v3, 1.0, v3
	v_rcp_f32_e32 v3, v3
	s_nop 0
	v_mul_f32_e32 v1, v1, v3
	v_mul_f32_e32 v1, v2, v1
	v_mul_f32_e32 v2, v83, v0
	v_mov_b64_e32 v[80:81], v[220:221]
	v_mov_b64_e32 v[82:83], v[222:223]
	v_mul_f32_e32 v3, 0xbfb8aa3b, v2
	v_exp_f32_e32 v3, v3
	v_mul_f32_e32 v0, v91, v0
	v_add_f32_e32 v3, 1.0, v3
	v_rcp_f32_e32 v3, v3
	s_nop 0
	v_mul_f32_e32 v2, v2, v3
	v_mul_f32_e32 v0, v0, v2
	v_cvt_pk_bf16_f32 v2, v1, v0
	v_mad_i64_i32 v[0:1], s[2:3], v156, s8, v[128:129]
	global_store_dword v[0:1], v2, off
	v_pk_fma_f32 v[0:1], v[80:81], s[12:13], v[130:131] op_sel_hi:[1,0,0]
	s_nop 0
	s_nop 0
	v_rsq_f32_e32 v0, v0
	s_nop 0
	v_mul_f32_e32 v2, v68, v0
	v_mul_f32_e32 v8, 0xbfb8aa3b, v2
	v_exp_f32_e32 v8, v8
	v_mul_f32_e32 v3, v76, v0
	v_add_f32_e32 v8, 1.0, v8
	v_rcp_f32_e32 v8, v8
	s_nop 0
	v_mul_f32_e32 v2, v2, v8
	v_mul_f32_e32 v2, v3, v2
	v_mul_f32_e32 v3, v64, v0
	v_mul_f32_e32 v8, 0xbfb8aa3b, v3
	v_exp_f32_e32 v8, v8
	v_mul_f32_e32 v0, v72, v0
	v_add_f32_e32 v8, 1.0, v8
	v_rcp_f32_e32 v8, v8
	s_nop 0
	v_mul_f32_e32 v3, v3, v8
	v_mul_f32_e32 v0, v0, v3
	v_cvt_pk_bf16_f32 v0, v2, v0
	global_store_dword v[84:85], v0, off
	v_rsq_f32_e32 v0, v1
	s_nop 0
	v_mul_f32_e32 v1, v69, v0
	v_mul_f32_e32 v3, 0xbfb8aa3b, v1
	v_exp_f32_e32 v3, v3
	v_mul_f32_e32 v2, v77, v0
	v_add_f32_e32 v3, 1.0, v3
	v_rcp_f32_e32 v3, v3
	s_nop 0
	v_mul_f32_e32 v1, v1, v3
	v_mul_f32_e32 v1, v2, v1
	v_mul_f32_e32 v2, v65, v0
	v_mul_f32_e32 v3, 0xbfb8aa3b, v2
	v_exp_f32_e32 v3, v3
	v_mul_f32_e32 v0, v73, v0
	v_mad_i64_i32 v[64:65], s[2:3], v151, s8, v[128:129]
	v_add_f32_e32 v3, 1.0, v3
	v_rcp_f32_e32 v3, v3
	s_nop 0
	v_mul_f32_e32 v2, v2, v3
	v_mul_f32_e32 v0, v0, v2
	v_cvt_pk_bf16_f32 v2, v1, v0
	v_mad_i64_i32 v[0:1], s[2:3], v154, s8, v[128:129]
	global_store_dword v[0:1], v2, off
	v_pk_fma_f32 v[2:3], v[82:83], s[12:13], v[130:131] op_sel_hi:[1,0,0]
	v_mad_i64_i32 v[0:1], s[2:3], v153, s8, v[128:129]
	s_nop 0
	v_rsq_f32_e32 v2, v2
	s_nop 0
	v_mul_f32_e32 v8, v70, v2
	v_mul_f32_e32 v10, 0xbfb8aa3b, v8
	v_exp_f32_e32 v10, v10
	v_mul_f32_e32 v9, v78, v2
	v_add_f32_e32 v10, 1.0, v10
	v_rcp_f32_e32 v10, v10
	s_nop 0
	v_mul_f32_e32 v8, v8, v10
	v_mul_f32_e32 v8, v9, v8
	v_mul_f32_e32 v9, v66, v2
	v_mul_f32_e32 v10, 0xbfb8aa3b, v9
	v_exp_f32_e32 v10, v10
	v_mul_f32_e32 v2, v74, v2
	v_add_f32_e32 v10, 1.0, v10
	v_rcp_f32_e32 v10, v10
	s_nop 0
	v_mul_f32_e32 v9, v9, v10
	v_mul_f32_e32 v2, v2, v9
	v_cvt_pk_bf16_f32 v2, v8, v2
	global_store_dword v[0:1], v2, off
	v_rsq_f32_e32 v0, v3
	s_nop 0
	v_mul_f32_e32 v1, v71, v0
	v_mul_f32_e32 v3, 0xbfb8aa3b, v1
	v_exp_f32_e32 v3, v3
	v_mul_f32_e32 v2, v79, v0
	v_add_f32_e32 v3, 1.0, v3
	v_rcp_f32_e32 v3, v3
	s_nop 0
	v_mul_f32_e32 v1, v1, v3
	v_mul_f32_e32 v1, v2, v1
	v_mul_f32_e32 v2, v67, v0
	v_mul_f32_e32 v3, 0xbfb8aa3b, v2
	v_exp_f32_e32 v3, v3
	v_mul_f32_e32 v0, v75, v0
	v_add_f32_e32 v3, 1.0, v3
	v_rcp_f32_e32 v3, v3
	s_nop 0
	v_mul_f32_e32 v2, v2, v3
	v_mul_f32_e32 v0, v0, v2
	v_cvt_pk_bf16_f32 v2, v1, v0
	v_mad_i64_i32 v[0:1], s[2:3], v152, s8, v[128:129]
	global_store_dword v[0:1], v2, off
	v_mov_b64_e32 v[0:1], v[224:225]
	v_mov_b64_e32 v[2:3], v[226:227]
	v_pk_fma_f32 v[0:1], v[0:1], s[12:13], v[130:131] op_sel_hi:[1,0,0]
	s_nop 0
	v_pk_fma_f32 v[2:3], v[2:3], s[12:13], v[130:131] op_sel_hi:[1,0,0]
	v_rsq_f32_e32 v0, v0
	s_nop 0
	v_mul_f32_e32 v8, v52, v0
	v_mul_f32_e32 v10, 0xbfb8aa3b, v8
	v_exp_f32_e32 v10, v10
	v_mul_f32_e32 v9, v60, v0
	v_add_f32_e32 v10, 1.0, v10
	v_rcp_f32_e32 v10, v10
	s_nop 0
	v_mul_f32_e32 v8, v8, v10
	v_mul_f32_e32 v8, v9, v8
	v_mul_f32_e32 v9, v48, v0
	v_mul_f32_e32 v10, 0xbfb8aa3b, v9
	v_exp_f32_e32 v10, v10
	v_mul_f32_e32 v0, v56, v0
	v_add_f32_e32 v10, 1.0, v10
	v_rcp_f32_e32 v10, v10
	s_nop 0
	v_mul_f32_e32 v9, v9, v10
	v_mul_f32_e32 v0, v0, v9
; __device__ __forceinline__ u32 pack2(float a, float b) { return (u32)f2bf(a) | ((u32)f2bf(b) << 16); }
; __device__ __forceinline__ float sigmoidf_(float x) { return __builtin_amdgcn_rcpf(1.f + __expf(-x)); }
; __device__ __forceinline__ void gemm_tile(const GemmArgs& ga, int wgid, int next_wgid, bool prefetched, u16* shm, unsigned char* ws, int wv_) {
;     ...
;     _Pragma("unroll") for (int ai = 0; ai < 2; ++ai)
;       _Pragma("unroll") for (int m = 0; m < 4; ++m)
;         _Pragma("unroll") for (int j = 0; j < 4; ++j) sc[ai][m][j] = e_ss[rbase + ai * HALF + m * 16 + j];
;     _Pragma("unroll") for (int ai = 0; ai < 2; ++ai)
;       _Pragma("unroll") for (int m = 0; m < 4; ++m)
;         _Pragma("unroll") for (int j = 0; j < 4; ++j) {
;           int row = rbase + ai * HALF + m * 16 + j;
;           float s = rsqrtf(sc[ai][m][j] * (1.f / D_) + 1e-6f);
;           float h2[2];
;           _Pragma("unroll") for (int n = 0; n < 2; ++n) {
;             float a1 = acc[ai][0][m][n][j] * s, a3 = acc[ai][1][m][n][j] * s;
;             h2[n] = a1 * sigmoidf_(a1) * a3;
;           }
;           *(u32*)(e_outb + (size_t)row * F_ + oc) = pack2(h2[0], h2[1]);
;         }
	v_cvt_pk_bf16_f32 v0, v8, v0
	global_store_dword v[64:65], v0, off
	v_rsq_f32_e32 v0, v1
	s_nop 0
	v_mul_f32_e32 v1, v53, v0
	v_mul_f32_e32 v9, 0xbfb8aa3b, v1
	v_exp_f32_e32 v9, v9
	v_mul_f32_e32 v8, v61, v0
	v_mad_i64_i32 v[52:53], s[2:3], v147, s8, v[128:129]
	v_add_f32_e32 v9, 1.0, v9
	v_rcp_f32_e32 v9, v9
	s_nop 0
	v_mul_f32_e32 v1, v1, v9
	v_mul_f32_e32 v1, v8, v1
	v_mul_f32_e32 v8, v49, v0
	v_mul_f32_e32 v9, 0xbfb8aa3b, v8
	v_exp_f32_e32 v9, v9
	v_mul_f32_e32 v0, v57, v0
	v_add_f32_e32 v9, 1.0, v9
	v_rcp_f32_e32 v9, v9
	s_nop 0
	v_mul_f32_e32 v8, v8, v9
	v_mul_f32_e32 v0, v0, v8
	v_cvt_pk_bf16_f32 v8, v1, v0
	v_mad_i64_i32 v[0:1], s[2:3], v150, s8, v[128:129]
	global_store_dword v[0:1], v8, off
	v_rsq_f32_e32 v2, v2
	v_mad_i64_i32 v[0:1], s[2:3], v149, s8, v[128:129]
	v_mul_f32_e32 v8, v54, v2
	v_mul_f32_e32 v10, 0xbfb8aa3b, v8
	v_exp_f32_e32 v10, v10
	v_mul_f32_e32 v9, v62, v2
	v_add_f32_e32 v10, 1.0, v10
	v_rcp_f32_e32 v10, v10
	s_nop 0
	v_mul_f32_e32 v8, v8, v10
	v_mul_f32_e32 v8, v9, v8
	v_mul_f32_e32 v9, v50, v2
	v_mul_f32_e32 v10, 0xbfb8aa3b, v9
	v_exp_f32_e32 v10, v10
	v_mul_f32_e32 v2, v58, v2
	v_add_f32_e32 v10, 1.0, v10
	v_rcp_f32_e32 v10, v10
	s_nop 0
	v_mul_f32_e32 v9, v9, v10
	v_mul_f32_e32 v2, v2, v9
	v_cvt_pk_bf16_f32 v2, v8, v2
	global_store_dword v[0:1], v2, off
	v_rsq_f32_e32 v0, v3
	s_nop 0
	v_mul_f32_e32 v1, v55, v0
	v_mul_f32_e32 v3, 0xbfb8aa3b, v1
	v_exp_f32_e32 v3, v3
	v_mul_f32_e32 v2, v63, v0
	v_add_f32_e32 v3, 1.0, v3
	v_rcp_f32_e32 v3, v3
	s_nop 0
	v_mul_f32_e32 v1, v1, v3
	v_mul_f32_e32 v1, v2, v1
	v_mul_f32_e32 v2, v51, v0
	v_mov_b64_e32 v[48:49], v[228:229]
	v_mov_b64_e32 v[50:51], v[230:231]
	v_mul_f32_e32 v3, 0xbfb8aa3b, v2
	v_exp_f32_e32 v3, v3
	v_mul_f32_e32 v0, v59, v0
	v_add_f32_e32 v3, 1.0, v3
	v_rcp_f32_e32 v3, v3
	s_nop 0
	v_mul_f32_e32 v2, v2, v3
	v_mul_f32_e32 v0, v0, v2
	v_cvt_pk_bf16_f32 v2, v1, v0
	v_mad_i64_i32 v[0:1], s[2:3], v148, s8, v[128:129]
	global_store_dword v[0:1], v2, off
	v_pk_fma_f32 v[0:1], v[48:49], s[12:13], v[130:131] op_sel_hi:[1,0,0]
	s_nop 0
	s_nop 0
	v_rsq_f32_e32 v0, v0
	s_nop 0
	v_mul_f32_e32 v2, v36, v0
	v_mul_f32_e32 v8, 0xbfb8aa3b, v2
	v_exp_f32_e32 v8, v8
	v_mul_f32_e32 v3, v44, v0
	v_add_f32_e32 v8, 1.0, v8
	v_rcp_f32_e32 v8, v8
	s_nop 0
	v_mul_f32_e32 v2, v2, v8
	v_mul_f32_e32 v2, v3, v2
	v_mul_f32_e32 v3, v32, v0
	v_mul_f32_e32 v8, 0xbfb8aa3b, v3
	v_exp_f32_e32 v8, v8
	v_mul_f32_e32 v0, v40, v0
	v_add_f32_e32 v8, 1.0, v8
	v_rcp_f32_e32 v8, v8
	s_nop 0
	v_mul_f32_e32 v3, v3, v8
	v_mul_f32_e32 v0, v0, v3
	v_cvt_pk_bf16_f32 v0, v2, v0
	global_store_dword v[52:53], v0, off
	v_rsq_f32_e32 v0, v1
	s_nop 0
	v_mul_f32_e32 v1, v37, v0
	v_mul_f32_e32 v3, 0xbfb8aa3b, v1
	v_exp_f32_e32 v3, v3
	v_mul_f32_e32 v2, v45, v0
	v_add_f32_e32 v3, 1.0, v3
	v_rcp_f32_e32 v3, v3
	s_nop 0
	v_mul_f32_e32 v1, v1, v3
	v_mul_f32_e32 v1, v2, v1
	v_mul_f32_e32 v2, v33, v0
	v_mul_f32_e32 v3, 0xbfb8aa3b, v2
	v_exp_f32_e32 v3, v3
	v_mul_f32_e32 v0, v41, v0
	v_mad_i64_i32 v[32:33], s[2:3], v143, s8, v[128:129]
	v_add_f32_e32 v3, 1.0, v3
	v_rcp_f32_e32 v3, v3
	s_nop 0
	v_mul_f32_e32 v2, v2, v3
	v_mul_f32_e32 v0, v0, v2
	v_cvt_pk_bf16_f32 v2, v1, v0
	v_mad_i64_i32 v[0:1], s[2:3], v146, s8, v[128:129]
	global_store_dword v[0:1], v2, off
	v_pk_fma_f32 v[2:3], v[50:51], s[12:13], v[130:131] op_sel_hi:[1,0,0]
	v_mad_i64_i32 v[0:1], s[2:3], v145, s8, v[128:129]
	s_nop 0
	v_rsq_f32_e32 v2, v2
	s_nop 0
	v_mul_f32_e32 v8, v38, v2
	v_mul_f32_e32 v10, 0xbfb8aa3b, v8
	v_exp_f32_e32 v10, v10
	v_mul_f32_e32 v9, v46, v2
	v_add_f32_e32 v10, 1.0, v10
	v_rcp_f32_e32 v10, v10
	s_nop 0
	v_mul_f32_e32 v8, v8, v10
	v_mul_f32_e32 v8, v9, v8
	v_mul_f32_e32 v9, v34, v2
	v_mul_f32_e32 v10, 0xbfb8aa3b, v9
	v_exp_f32_e32 v10, v10
	v_mul_f32_e32 v2, v42, v2
	v_add_f32_e32 v10, 1.0, v10
	v_rcp_f32_e32 v10, v10
	s_nop 0
	v_mul_f32_e32 v9, v9, v10
	v_mul_f32_e32 v2, v2, v9
	v_cvt_pk_bf16_f32 v2, v8, v2
	global_store_dword v[0:1], v2, off
	v_rsq_f32_e32 v0, v3
	s_nop 0
	v_mul_f32_e32 v1, v39, v0
	v_mul_f32_e32 v3, 0xbfb8aa3b, v1
	v_exp_f32_e32 v3, v3
	v_mul_f32_e32 v2, v47, v0
	v_add_f32_e32 v3, 1.0, v3
	v_rcp_f32_e32 v3, v3
	s_nop 0
	v_mul_f32_e32 v1, v1, v3
	v_mul_f32_e32 v1, v2, v1
	v_mul_f32_e32 v2, v35, v0
	v_mul_f32_e32 v3, 0xbfb8aa3b, v2
	v_exp_f32_e32 v3, v3
	v_mul_f32_e32 v0, v43, v0
	v_add_f32_e32 v3, 1.0, v3
	v_rcp_f32_e32 v3, v3
	s_nop 0
	v_mul_f32_e32 v2, v2, v3
	v_mul_f32_e32 v0, v0, v2
	v_cvt_pk_bf16_f32 v2, v1, v0
	v_mad_i64_i32 v[0:1], s[2:3], v144, s8, v[128:129]
	global_store_dword v[0:1], v2, off
	v_mov_b64_e32 v[0:1], v[232:233]
	v_mov_b64_e32 v[2:3], v[234:235]
	v_pk_fma_f32 v[0:1], v[0:1], s[12:13], v[130:131] op_sel_hi:[1,0,0]
	s_nop 0
	v_pk_fma_f32 v[2:3], v[2:3], s[12:13], v[130:131] op_sel_hi:[1,0,0]
	v_rsq_f32_e32 v0, v0
	s_nop 0
	v_mul_f32_e32 v8, v20, v0
	v_mul_f32_e32 v10, 0xbfb8aa3b, v8
	v_exp_f32_e32 v10, v10
	v_mul_f32_e32 v9, v244, v0
; __device__ __forceinline__ u32 pack2(float a, float b) { return (u32)f2bf(a) | ((u32)f2bf(b) << 16); }
; __device__ __forceinline__ float sigmoidf_(float x) { return __builtin_amdgcn_rcpf(1.f + __expf(-x)); }
; __device__ __forceinline__ void gemm_tile(const GemmArgs& ga, int wgid, int next_wgid, bool prefetched, u16* shm, unsigned char* ws, int wv_) {
;     ...
;     _Pragma("unroll") for (int ai = 0; ai < 2; ++ai)
;       _Pragma("unroll") for (int m = 0; m < 4; ++m)
;         _Pragma("unroll") for (int j = 0; j < 4; ++j) sc[ai][m][j] = e_ss[rbase + ai * HALF + m * 16 + j];
;     _Pragma("unroll") for (int ai = 0; ai < 2; ++ai)
;       _Pragma("unroll") for (int m = 0; m < 4; ++m)
;         _Pragma("unroll") for (int j = 0; j < 4; ++j) {
;           int row = rbase + ai * HALF + m * 16 + j;
;           float s = rsqrtf(sc[ai][m][j] * (1.f / D_) + 1e-6f);
;           float h2[2];
;           _Pragma("unroll") for (int n = 0; n < 2; ++n) {
;             float a1 = acc[ai][0][m][n][j] * s, a3 = acc[ai][1][m][n][j] * s;
;             h2[n] = a1 * sigmoidf_(a1) * a3;
;           }
;           *(u32*)(e_outb + (size_t)row * F_ + oc) = pack2(h2[0], h2[1]);
;         }
	v_add_f32_e32 v10, 1.0, v10
	v_rcp_f32_e32 v10, v10
	s_nop 0
	v_mul_f32_e32 v8, v8, v10
	v_mul_f32_e32 v8, v9, v8
	v_mul_f32_e32 v9, v240, v0
	v_mul_f32_e32 v10, 0xbfb8aa3b, v9
	v_exp_f32_e32 v10, v10
	v_mul_f32_e32 v0, v24, v0
	v_add_f32_e32 v10, 1.0, v10
	v_rcp_f32_e32 v10, v10
	s_nop 0
	v_mul_f32_e32 v9, v9, v10
	v_mul_f32_e32 v0, v0, v9
	v_cvt_pk_bf16_f32 v0, v8, v0
	global_store_dword v[32:33], v0, off
	v_rsq_f32_e32 v0, v1
	s_nop 0
	v_mul_f32_e32 v1, v21, v0
	v_mul_f32_e32 v9, 0xbfb8aa3b, v1
	v_exp_f32_e32 v9, v9
	v_mul_f32_e32 v8, v245, v0
	v_mad_i64_i32 v[20:21], s[2:3], v139, s8, v[128:129]
	v_add_f32_e32 v9, 1.0, v9
	v_rcp_f32_e32 v9, v9
	s_nop 0
	v_mul_f32_e32 v1, v1, v9
	v_mul_f32_e32 v1, v8, v1
	v_mul_f32_e32 v8, v241, v0
	v_mul_f32_e32 v9, 0xbfb8aa3b, v8
	v_exp_f32_e32 v9, v9
	v_mul_f32_e32 v0, v25, v0
	v_add_f32_e32 v9, 1.0, v9
	v_rcp_f32_e32 v9, v9
	s_nop 0
	v_mul_f32_e32 v8, v8, v9
	v_mul_f32_e32 v0, v0, v8
	v_cvt_pk_bf16_f32 v8, v1, v0
	v_mad_i64_i32 v[0:1], s[2:3], v142, s8, v[128:129]
	global_store_dword v[0:1], v8, off
	v_rsq_f32_e32 v2, v2
	v_mad_i64_i32 v[0:1], s[2:3], v141, s8, v[128:129]
	v_mul_f32_e32 v8, v22, v2
	v_mul_f32_e32 v10, 0xbfb8aa3b, v8
	v_exp_f32_e32 v10, v10
	v_mul_f32_e32 v9, v246, v2
	v_add_f32_e32 v10, 1.0, v10
	v_rcp_f32_e32 v10, v10
	s_nop 0
	v_mul_f32_e32 v8, v8, v10
	v_mul_f32_e32 v8, v9, v8
	v_mul_f32_e32 v9, v242, v2
	v_mul_f32_e32 v10, 0xbfb8aa3b, v9
	v_exp_f32_e32 v10, v10
	v_mul_f32_e32 v2, v26, v2
	v_add_f32_e32 v10, 1.0, v10
	v_rcp_f32_e32 v10, v10
	s_nop 0
	v_mul_f32_e32 v9, v9, v10
	v_mul_f32_e32 v2, v2, v9
	v_cvt_pk_bf16_f32 v2, v8, v2
	global_store_dword v[0:1], v2, off
	v_rsq_f32_e32 v0, v3
	s_nop 0
	v_mul_f32_e32 v1, v23, v0
	v_mul_f32_e32 v3, 0xbfb8aa3b, v1
	v_exp_f32_e32 v3, v3
	v_mul_f32_e32 v2, v247, v0
	v_add_f32_e32 v3, 1.0, v3
	v_rcp_f32_e32 v3, v3
	s_nop 0
	v_mul_f32_e32 v1, v1, v3
	v_mul_f32_e32 v1, v2, v1
	v_mul_f32_e32 v2, v243, v0
	v_mul_f32_e32 v3, 0xbfb8aa3b, v2
	v_exp_f32_e32 v3, v3
	v_mul_f32_e32 v0, v27, v0
	v_add_f32_e32 v3, 1.0, v3
	v_rcp_f32_e32 v3, v3
	s_nop 0
	v_mul_f32_e32 v2, v2, v3
	v_mul_f32_e32 v0, v0, v2
	v_cvt_pk_bf16_f32 v2, v1, v0
	v_mad_i64_i32 v[0:1], s[2:3], v140, s8, v[128:129]
	global_store_dword v[0:1], v2, off
	v_pk_fma_f32 v[0:1], v[16:17], s[12:13], v[130:131] op_sel_hi:[1,0,0]
	s_nop 0
	s_nop 0
	v_rsq_f32_e32 v0, v0
	s_nop 0
	v_mul_f32_e32 v2, v204, v0
	v_mul_f32_e32 v8, 0xbfb8aa3b, v2
	v_exp_f32_e32 v8, v8
	v_mul_f32_e32 v3, v12, v0
	v_add_f32_e32 v8, 1.0, v8
	v_rcp_f32_e32 v8, v8
	s_nop 0
	v_mul_f32_e32 v2, v2, v8
	v_mul_f32_e32 v2, v3, v2
	v_mul_f32_e32 v3, v182, v0
	v_mul_f32_e32 v0, v4, v0
	v_mul_f32_e32 v4, 0xbfb8aa3b, v3
	v_exp_f32_e32 v4, v4
	s_nop 0
	v_add_f32_e32 v4, 1.0, v4
	v_rcp_f32_e32 v4, v4
	s_nop 0
	v_mul_f32_e32 v3, v3, v4
	v_mul_f32_e32 v0, v0, v3
	v_cvt_pk_bf16_f32 v0, v2, v0
	global_store_dword v[20:21], v0, off
	v_rsq_f32_e32 v0, v1
	s_nop 0
	v_mul_f32_e32 v1, v205, v0
	v_mul_f32_e32 v3, 0xbfb8aa3b, v1
	v_exp_f32_e32 v3, v3
	v_mul_f32_e32 v2, v13, v0
	v_add_f32_e32 v3, 1.0, v3
	v_rcp_f32_e32 v3, v3
	s_nop 0
	v_mul_f32_e32 v1, v1, v3
	v_mul_f32_e32 v1, v2, v1
	v_mul_f32_e32 v2, v183, v0
	v_mul_f32_e32 v3, 0xbfb8aa3b, v2
	v_exp_f32_e32 v3, v3
	v_mul_f32_e32 v0, v5, v0
	v_add_f32_e32 v3, 1.0, v3
	v_rcp_f32_e32 v3, v3
	s_nop 0
	v_mul_f32_e32 v2, v2, v3
	v_mul_f32_e32 v0, v0, v2
	v_cvt_pk_bf16_f32 v2, v1, v0
	v_mad_i64_i32 v[0:1], s[2:3], v138, s8, v[128:129]
	global_store_dword v[0:1], v2, off
	v_pk_fma_f32 v[2:3], v[18:19], s[12:13], v[130:131] op_sel_hi:[1,0,0]
	v_mad_i64_i32 v[0:1], s[2:3], v137, s8, v[128:129]
	s_nop 0
	v_rsq_f32_e32 v2, v2
	s_nop 0
	v_mul_f32_e32 v4, v206, v2
	v_mul_f32_e32 v8, 0xbfb8aa3b, v4
	v_exp_f32_e32 v8, v8
	v_mul_f32_e32 v5, v14, v2
	v_add_f32_e32 v8, 1.0, v8
	v_rcp_f32_e32 v8, v8
	s_nop 0
	v_mul_f32_e32 v4, v4, v8
	v_mul_f32_e32 v4, v5, v4
	v_mul_f32_e32 v5, v184, v2
	v_mul_f32_e32 v2, v6, v2
	v_mul_f32_e32 v6, 0xbfb8aa3b, v5
	v_exp_f32_e32 v6, v6
	s_nop 0
	v_add_f32_e32 v6, 1.0, v6
	v_rcp_f32_e32 v6, v6
	s_nop 0
	v_mul_f32_e32 v5, v5, v6
	v_mul_f32_e32 v2, v2, v5
	v_cvt_pk_bf16_f32 v2, v4, v2
	global_store_dword v[0:1], v2, off
	v_rsq_f32_e32 v0, v3
	s_nop 0
	v_mul_f32_e32 v1, v207, v0
	v_mul_f32_e32 v3, 0xbfb8aa3b, v1
	v_exp_f32_e32 v3, v3
	v_mul_f32_e32 v2, v15, v0
	v_add_f32_e32 v3, 1.0, v3
	v_rcp_f32_e32 v3, v3
	s_nop 0
	v_mul_f32_e32 v1, v1, v3
	v_mul_f32_e32 v1, v2, v1
	v_mul_f32_e32 v2, v185, v0
	v_mul_f32_e32 v3, 0xbfb8aa3b, v2
	v_exp_f32_e32 v3, v3
	v_mul_f32_e32 v0, v7, v0
	v_add_f32_e32 v3, 1.0, v3
	v_rcp_f32_e32 v3, v3
	s_nop 0
	v_mul_f32_e32 v2, v2, v3
	v_mul_f32_e32 v0, v0, v2
	v_bfe_u32 v2, v1, 16, 1
	v_add3_u32 v1, v1, v2, s48
	v_bfe_u32 v2, v0, 16, 1
	v_lshrrev_b32_e32 v1, 16, v1
	v_add3_u32 v0, v0, v2, s48
	v_and_or_b32 v2, v0, s97, v1
	v_mad_i64_i32 v[0:1], s[2:3], v136, s8, v[128:129]
	global_store_dword v[0:1], v2, off
	s_branch .LBB0_501
